# adds: first K-loop iteration of P2/P5 peeled with C=0 (no accumulator zeroing movs), P4 sticky-timeout load no longer waited at phase start; on top of the P0 load-pipelining changes
# speedup vs baseline: 1.0109x; 1.0055x over previous
.LBB0_244:
	s_ashr_i32 s73, s72, 31
	s_lshl_b64 s[74:75], s[72:73], 19
	s_add_u32 s74, s24, s74
	s_addc_u32 s75, s25, s75
	s_and_b64 s[76:77], s[4:5], exec
	s_cselect_b32 s0, s75, s81
	s_cselect_b32 s7, s74, s80
	s_ashr_i32 s47, s46, 31
	s_lshl_b64 s[76:77], s[46:47], 19
	s_add_u32 s76, s70, s76
	s_addc_u32 s77, s71, s77
	s_and_b64 s[84:85], s[4:5], exec
	s_cselect_b32 s47, s77, s83
	s_cselect_b32 s73, s76, s82
	s_add_u32 s80, s80, 0x40080
	s_addc_u32 s81, s81, 0
	s_add_u32 s93, s82, 0x100
	s_addc_u32 s94, s83, 0
	s_mov_b32 s95, -2
	ds_read_b128 v[130:133], v161
	ds_read_b128 v[134:137], v161 offset:1024
	ds_read_b128 v[164:167], v161 offset:2048
	ds_read_b128 v[168:171], v161 offset:3072
	ds_read_b128 v[172:175], v162
	ds_read_b128 v[176:179], v162 offset:1024
	ds_read_b128 v[180:183], v162 offset:2048
	ds_read_b128 v[184:187], v162 offset:3072
	s_add_u32 s82, s80, 0xfffc0080
	s_addc_u32 s83, s81, -1
	s_cmp_eq_u32 s95, 12
	s_cselect_b32 s85, s0, s83
	s_cselect_b32 s84, s7, s82
	s_cselect_b32 s83, s47, s94
	s_cselect_b32 s82, s73, s93
	v_lshl_add_u64 v[220:221], s[80:81], 0, v[150:151]
	s_add_i32 m0, s27, 0xc000
	ds_read_b128 v[188:191], v163
	ds_read_b128 v[192:195], v163 offset:1024
	ds_read_b128 v[196:199], v163 offset:2048
	ds_read_b128 v[200:203], v163 offset:3072
	ds_read_b128 v[204:207], v163 offset:4096
	ds_read_b128 v[208:211], v163 offset:5120
	ds_read_b128 v[212:215], v163 offset:6144
	ds_read_b128 v[216:219], v163 offset:7168
	global_load_lds_dwordx4 v[220:221], off
	v_lshl_add_u64 v[220:221], s[80:81], 0, v[152:153]
	s_add_i32 m0, s27, 0xe000
	s_nop 0
	global_load_lds_dwordx4 v[220:221], off
	s_waitcnt vmcnt(8)
	s_waitcnt lgkmcnt(0)
	s_setprio 1
	s_waitcnt lgkmcnt(0)
	v_mfma_f32_16x16x32_bf16 v[126:129], v[130:133], v[188:191], 0
	s_barrier
	v_mfma_f32_16x16x32_bf16 v[122:125], v[164:167], v[188:191], 0
	v_mfma_f32_16x16x32_bf16 v[118:121], v[130:133], v[196:199], 0
	v_mfma_f32_16x16x32_bf16 v[110:113], v[164:167], v[196:199], 0
	v_mfma_f32_16x16x32_bf16 v[102:105], v[130:133], v[204:207], 0
	v_mfma_f32_16x16x32_bf16 v[94:97], v[164:167], v[204:207], 0
	v_mfma_f32_16x16x32_bf16 v[86:89], v[130:133], v[212:215], 0
	v_mfma_f32_16x16x32_bf16 v[78:81], v[164:167], v[212:215], 0
	v_mfma_f32_16x16x32_bf16 v[114:117], v[172:175], v[188:191], 0
	v_mfma_f32_16x16x32_bf16 v[106:109], v[180:183], v[188:191], 0
	v_mfma_f32_16x16x32_bf16 v[98:101], v[172:175], v[196:199], 0
	v_mfma_f32_16x16x32_bf16 v[90:93], v[180:183], v[196:199], 0
	v_mfma_f32_16x16x32_bf16 v[82:85], v[172:175], v[204:207], 0
	v_mfma_f32_16x16x32_bf16 v[74:77], v[180:183], v[204:207], 0
	v_mfma_f32_16x16x32_bf16 v[70:73], v[172:175], v[212:215], 0
	v_mfma_f32_16x16x32_bf16 v[66:69], v[180:183], v[212:215], 0
	v_mfma_f32_16x16x32_bf16 v[126:129], v[134:137], v[192:195], v[126:129]
	v_mfma_f32_16x16x32_bf16 v[122:125], v[168:171], v[192:195], v[122:125]
	v_mfma_f32_16x16x32_bf16 v[118:121], v[134:137], v[200:203], v[118:121]
	v_mfma_f32_16x16x32_bf16 v[110:113], v[168:171], v[200:203], v[110:113]
	v_mfma_f32_16x16x32_bf16 v[102:105], v[134:137], v[208:211], v[102:105]
	v_mfma_f32_16x16x32_bf16 v[94:97], v[168:171], v[208:211], v[94:97]
	v_mfma_f32_16x16x32_bf16 v[86:89], v[134:137], v[216:219], v[86:89]
	v_mfma_f32_16x16x32_bf16 v[78:81], v[168:171], v[216:219], v[78:81]
	v_mfma_f32_16x16x32_bf16 v[114:117], v[176:179], v[192:195], v[114:117]
	v_mfma_f32_16x16x32_bf16 v[106:109], v[184:187], v[192:195], v[106:109]
	v_mfma_f32_16x16x32_bf16 v[98:101], v[176:179], v[200:203], v[98:101]
	v_mfma_f32_16x16x32_bf16 v[90:93], v[184:187], v[200:203], v[90:93]
	v_mfma_f32_16x16x32_bf16 v[82:85], v[176:179], v[208:211], v[82:85]
	v_mfma_f32_16x16x32_bf16 v[74:77], v[184:187], v[208:211], v[74:77]
	v_mfma_f32_16x16x32_bf16 v[70:73], v[176:179], v[216:219], v[70:73]
	v_mfma_f32_16x16x32_bf16 v[66:69], v[184:187], v[216:219], v[66:69]
	s_setprio 0
	s_barrier
	s_add_i32 s96, s90, s26
	v_lshl_add_u64 v[220:221], s[82:83], 0, v[140:141]
	s_mov_b32 m0, s96
	ds_read_b128 v[188:191], v163 offset:16384
	ds_read_b128 v[192:195], v163 offset:17408
	ds_read_b128 v[196:199], v163 offset:18432
	ds_read_b128 v[200:203], v163 offset:19456
	ds_read_b128 v[204:207], v163 offset:20480
	ds_read_b128 v[208:211], v163 offset:21504
	ds_read_b128 v[212:215], v163 offset:22528
	ds_read_b128 v[216:219], v163 offset:23552
	global_load_lds_dwordx4 v[220:221], off
	s_add_i32 m0, s96, 0x2000
	s_add_u32 s96, s82, 0x40000
	v_lshl_add_u64 v[222:223], s[82:83], 0, v[144:145]
	s_addc_u32 s97, s83, 0
	s_add_i32 s98, s91, s26
	global_load_lds_dwordx4 v[222:223], off
	v_lshl_add_u64 v[224:225], s[96:97], 0, v[140:141]
	s_mov_b32 m0, s98
	v_lshl_add_u64 v[226:227], s[84:85], 0, v[142:143]
	global_load_lds_dwordx4 v[224:225], off
	v_lshl_add_u64 v[224:225], s[96:97], 0, v[144:145]
	s_add_i32 m0, s98, 0x2000
	s_nop 0
	global_load_lds_dwordx4 v[224:225], off
	v_lshl_add_u64 v[224:225], s[84:85], 0, v[138:139]
	s_mov_b32 m0, s27
	s_nop 0
	global_load_lds_dwordx4 v[224:225], off
	s_mov_b32 m0, s28
	s_nop 0
	global_load_lds_dwordx4 v[226:227], off
	s_waitcnt vmcnt(8)
	s_waitcnt lgkmcnt(0)
	s_setprio 1
	s_waitcnt lgkmcnt(0)
	v_mfma_f32_16x16x32_bf16 v[62:65], v[130:133], v[188:191], 0
	s_barrier
	v_mfma_f32_16x16x32_bf16 v[58:61], v[164:167], v[188:191], 0
	v_mfma_f32_16x16x32_bf16 v[54:57], v[130:133], v[196:199], 0
	v_mfma_f32_16x16x32_bf16 v[46:49], v[164:167], v[196:199], 0
	v_mfma_f32_16x16x32_bf16 v[38:41], v[130:133], v[204:207], 0
	v_mfma_f32_16x16x32_bf16 v[30:33], v[164:167], v[204:207], 0
	v_mfma_f32_16x16x32_bf16 v[22:25], v[130:133], v[212:215], 0
	v_mfma_f32_16x16x32_bf16 v[14:17], v[164:167], v[212:215], 0
	v_mfma_f32_16x16x32_bf16 v[50:53], v[172:175], v[188:191], 0
	v_mfma_f32_16x16x32_bf16 v[42:45], v[180:183], v[188:191], 0
	v_mfma_f32_16x16x32_bf16 v[34:37], v[172:175], v[196:199], 0
	v_mfma_f32_16x16x32_bf16 v[26:29], v[180:183], v[196:199], 0
	v_mfma_f32_16x16x32_bf16 v[18:21], v[172:175], v[204:207], 0
	v_mfma_f32_16x16x32_bf16 v[10:13], v[180:183], v[204:207], 0
	v_mfma_f32_16x16x32_bf16 v[6:9], v[172:175], v[212:215], 0
	v_mfma_f32_16x16x32_bf16 v[2:5], v[180:183], v[212:215], 0
	v_mfma_f32_16x16x32_bf16 v[62:65], v[134:137], v[192:195], v[62:65]
	v_mfma_f32_16x16x32_bf16 v[58:61], v[168:171], v[192:195], v[58:61]
	v_mfma_f32_16x16x32_bf16 v[54:57], v[134:137], v[200:203], v[54:57]
	v_mfma_f32_16x16x32_bf16 v[46:49], v[168:171], v[200:203], v[46:49]
	v_mfma_f32_16x16x32_bf16 v[38:41], v[134:137], v[208:211], v[38:41]
	v_mfma_f32_16x16x32_bf16 v[30:33], v[168:171], v[208:211], v[30:33]
	v_mfma_f32_16x16x32_bf16 v[22:25], v[134:137], v[216:219], v[22:25]
	v_mfma_f32_16x16x32_bf16 v[14:17], v[168:171], v[216:219], v[14:17]
	v_mfma_f32_16x16x32_bf16 v[50:53], v[176:179], v[192:195], v[50:53]
	v_mfma_f32_16x16x32_bf16 v[42:45], v[184:187], v[192:195], v[42:45]
	v_mfma_f32_16x16x32_bf16 v[34:37], v[176:179], v[200:203], v[34:37]
	v_mfma_f32_16x16x32_bf16 v[26:29], v[184:187], v[200:203], v[26:29]
	v_mfma_f32_16x16x32_bf16 v[18:21], v[176:179], v[208:211], v[18:21]
	v_mfma_f32_16x16x32_bf16 v[10:13], v[184:187], v[208:211], v[10:13]
	v_mfma_f32_16x16x32_bf16 v[6:9], v[176:179], v[216:219], v[6:9]
	v_mfma_f32_16x16x32_bf16 v[2:5], v[184:187], v[216:219], v[2:5]
	s_setprio 0
	s_barrier
	s_add_i32 s96, 0, 0x18000
	v_add_u32_e32 v146, s96, v160
	s_add_i32 s97, 0, 0x1c000
	ds_read_b128 v[130:133], v146
	ds_read_b128 v[134:137], v146 offset:1024
	ds_read_b128 v[164:167], v146 offset:2048
	ds_read_b128 v[168:171], v146 offset:3072
	v_add_u32_e32 v146, s97, v160
	ds_read_b128 v[172:175], v146
	ds_read_b128 v[176:179], v146 offset:1024
	ds_read_b128 v[180:183], v146 offset:2048
	ds_read_b128 v[184:187], v146 offset:3072
	s_add_u32 s84, s84, 0x40000
	s_addc_u32 s85, s85, 0
	s_mov_b32 m0, s29
	v_lshl_add_u64 v[228:229], s[84:85], 0, v[138:139]
	ds_read_b128 v[188:191], v163 offset:32768
	ds_read_b128 v[192:195], v163 offset:33792
	ds_read_b128 v[196:199], v163 offset:34816
	ds_read_b128 v[200:203], v163 offset:35840
	ds_read_b128 v[204:207], v163 offset:36864
	ds_read_b128 v[208:211], v163 offset:37888
	ds_read_b128 v[212:215], v163 offset:38912
	ds_read_b128 v[216:219], v163 offset:39936
	global_load_lds_dwordx4 v[228:229], off
	v_lshl_add_u64 v[228:229], s[84:85], 0, v[142:143]
	s_mov_b32 m0, s79
	s_nop 0
	global_load_lds_dwordx4 v[228:229], off
	s_waitcnt vmcnt(8)
	s_waitcnt lgkmcnt(0)
	s_setprio 1
	s_waitcnt lgkmcnt(0)
	v_mfma_f32_16x16x32_bf16 v[126:129], v[130:133], v[188:191], v[126:129]
	s_barrier
	v_mfma_f32_16x16x32_bf16 v[122:125], v[164:167], v[188:191], v[122:125]
	v_mfma_f32_16x16x32_bf16 v[118:121], v[130:133], v[196:199], v[118:121]
	v_mfma_f32_16x16x32_bf16 v[110:113], v[164:167], v[196:199], v[110:113]
	v_mfma_f32_16x16x32_bf16 v[102:105], v[130:133], v[204:207], v[102:105]
	v_mfma_f32_16x16x32_bf16 v[94:97], v[164:167], v[204:207], v[94:97]
	v_mfma_f32_16x16x32_bf16 v[86:89], v[130:133], v[212:215], v[86:89]
	v_mfma_f32_16x16x32_bf16 v[78:81], v[164:167], v[212:215], v[78:81]
	v_mfma_f32_16x16x32_bf16 v[114:117], v[172:175], v[188:191], v[114:117]
	v_mfma_f32_16x16x32_bf16 v[106:109], v[180:183], v[188:191], v[106:109]
	v_mfma_f32_16x16x32_bf16 v[98:101], v[172:175], v[196:199], v[98:101]
	v_mfma_f32_16x16x32_bf16 v[90:93], v[180:183], v[196:199], v[90:93]
	v_mfma_f32_16x16x32_bf16 v[82:85], v[172:175], v[204:207], v[82:85]
	v_mfma_f32_16x16x32_bf16 v[74:77], v[180:183], v[204:207], v[74:77]
	v_mfma_f32_16x16x32_bf16 v[70:73], v[172:175], v[212:215], v[70:73]
	v_mfma_f32_16x16x32_bf16 v[66:69], v[180:183], v[212:215], v[66:69]
	v_mfma_f32_16x16x32_bf16 v[126:129], v[134:137], v[192:195], v[126:129]
	v_mfma_f32_16x16x32_bf16 v[122:125], v[168:171], v[192:195], v[122:125]
	v_mfma_f32_16x16x32_bf16 v[118:121], v[134:137], v[200:203], v[118:121]
	v_mfma_f32_16x16x32_bf16 v[110:113], v[168:171], v[200:203], v[110:113]
	v_mfma_f32_16x16x32_bf16 v[102:105], v[134:137], v[208:211], v[102:105]
	v_mfma_f32_16x16x32_bf16 v[94:97], v[168:171], v[208:211], v[94:97]
	v_mfma_f32_16x16x32_bf16 v[86:89], v[134:137], v[216:219], v[86:89]
	v_mfma_f32_16x16x32_bf16 v[78:81], v[168:171], v[216:219], v[78:81]
	v_mfma_f32_16x16x32_bf16 v[114:117], v[176:179], v[192:195], v[114:117]
	v_mfma_f32_16x16x32_bf16 v[106:109], v[184:187], v[192:195], v[106:109]
	v_mfma_f32_16x16x32_bf16 v[98:101], v[176:179], v[200:203], v[98:101]
	v_mfma_f32_16x16x32_bf16 v[90:93], v[184:187], v[200:203], v[90:93]
	v_mfma_f32_16x16x32_bf16 v[82:85], v[176:179], v[208:211], v[82:85]
	v_mfma_f32_16x16x32_bf16 v[74:77], v[184:187], v[208:211], v[74:77]
	v_mfma_f32_16x16x32_bf16 v[70:73], v[176:179], v[216:219], v[70:73]
	v_mfma_f32_16x16x32_bf16 v[66:69], v[184:187], v[216:219], v[66:69]
	s_setprio 0
	s_barrier
	s_add_i32 s84, s96, s26
	v_lshl_add_u64 v[220:221], v[220:221], 0, s[40:41]
	s_mov_b32 m0, s84
	ds_read_b128 v[188:191], v163 offset:49152
	ds_read_b128 v[192:195], v163 offset:50176
	ds_read_b128 v[196:199], v163 offset:51200
	ds_read_b128 v[200:203], v163 offset:52224
	ds_read_b128 v[204:207], v163 offset:53248
	ds_read_b128 v[208:211], v163 offset:54272
	ds_read_b128 v[212:215], v163 offset:55296
	ds_read_b128 v[216:219], v163 offset:56320
	global_load_lds_dwordx4 v[220:221], off
	s_add_i32 m0, s84, 0x2000
	s_add_u32 s82, s82, 0x40080
	v_lshl_add_u64 v[220:221], v[222:223], 0, s[40:41]
	s_addc_u32 s83, s83, 0
	s_add_i32 s84, s97, s26
	global_load_lds_dwordx4 v[220:221], off
	v_lshl_add_u64 v[220:221], s[82:83], 0, v[140:141]
	s_mov_b32 m0, s84
	s_nop 0
	global_load_lds_dwordx4 v[220:221], off
	v_lshl_add_u64 v[220:221], s[82:83], 0, v[144:145]
	s_add_i32 m0, s84, 0x2000
	s_nop 0
	global_load_lds_dwordx4 v[220:221], off
	v_lshl_add_u64 v[220:221], v[224:225], 0, s[40:41]
	s_mov_b32 m0, s87
	s_nop 0
	global_load_lds_dwordx4 v[220:221], off
	v_lshl_add_u64 v[220:221], v[226:227], 0, s[40:41]
	s_mov_b32 m0, s88
	s_nop 0
	global_load_lds_dwordx4 v[220:221], off
	s_waitcnt vmcnt(8)
	s_waitcnt lgkmcnt(0)
	s_setprio 1
	s_waitcnt lgkmcnt(0)
	v_mfma_f32_16x16x32_bf16 v[62:65], v[130:133], v[188:191], v[62:65]
	s_barrier
	v_mfma_f32_16x16x32_bf16 v[58:61], v[164:167], v[188:191], v[58:61]
	v_mfma_f32_16x16x32_bf16 v[54:57], v[130:133], v[196:199], v[54:57]
	v_mfma_f32_16x16x32_bf16 v[46:49], v[164:167], v[196:199], v[46:49]
	v_mfma_f32_16x16x32_bf16 v[38:41], v[130:133], v[204:207], v[38:41]
	v_mfma_f32_16x16x32_bf16 v[30:33], v[164:167], v[204:207], v[30:33]
	v_mfma_f32_16x16x32_bf16 v[22:25], v[130:133], v[212:215], v[22:25]
	v_mfma_f32_16x16x32_bf16 v[14:17], v[164:167], v[212:215], v[14:17]
	v_mfma_f32_16x16x32_bf16 v[50:53], v[172:175], v[188:191], v[50:53]
	v_mfma_f32_16x16x32_bf16 v[42:45], v[180:183], v[188:191], v[42:45]
	v_mfma_f32_16x16x32_bf16 v[34:37], v[172:175], v[196:199], v[34:37]
	v_mfma_f32_16x16x32_bf16 v[26:29], v[180:183], v[196:199], v[26:29]
	v_mfma_f32_16x16x32_bf16 v[18:21], v[172:175], v[204:207], v[18:21]
	v_mfma_f32_16x16x32_bf16 v[10:13], v[180:183], v[204:207], v[10:13]
	v_mfma_f32_16x16x32_bf16 v[6:9], v[172:175], v[212:215], v[6:9]
	v_mfma_f32_16x16x32_bf16 v[2:5], v[180:183], v[212:215], v[2:5]
	v_mfma_f32_16x16x32_bf16 v[62:65], v[134:137], v[192:195], v[62:65]
	v_mfma_f32_16x16x32_bf16 v[58:61], v[168:171], v[192:195], v[58:61]
	v_mfma_f32_16x16x32_bf16 v[54:57], v[134:137], v[200:203], v[54:57]
	v_mfma_f32_16x16x32_bf16 v[46:49], v[168:171], v[200:203], v[46:49]
	v_mfma_f32_16x16x32_bf16 v[38:41], v[134:137], v[208:211], v[38:41]
	v_mfma_f32_16x16x32_bf16 v[30:33], v[168:171], v[208:211], v[30:33]
	v_mfma_f32_16x16x32_bf16 v[22:25], v[134:137], v[216:219], v[22:25]
	v_mfma_f32_16x16x32_bf16 v[14:17], v[168:171], v[216:219], v[14:17]
	v_mfma_f32_16x16x32_bf16 v[50:53], v[176:179], v[192:195], v[50:53]
	v_mfma_f32_16x16x32_bf16 v[42:45], v[184:187], v[192:195], v[42:45]
	v_mfma_f32_16x16x32_bf16 v[34:37], v[176:179], v[200:203], v[34:37]
	v_mfma_f32_16x16x32_bf16 v[26:29], v[184:187], v[200:203], v[26:29]
	v_mfma_f32_16x16x32_bf16 v[18:21], v[176:179], v[208:211], v[18:21]
	v_mfma_f32_16x16x32_bf16 v[10:13], v[184:187], v[208:211], v[10:13]
	v_mfma_f32_16x16x32_bf16 v[6:9], v[176:179], v[216:219], v[6:9]
	v_mfma_f32_16x16x32_bf16 v[2:5], v[184:187], v[216:219], v[2:5]
	s_setprio 0
	s_barrier
	s_add_i32 s95, s95, 2
	s_add_u32 s80, s80, 0x100
	s_addc_u32 s81, s81, 0
	s_add_u32 s93, s93, 0x100
	s_addc_u32 s94, s94, 0
	s_cmp_gt_u32 s95, 13
	s_cbranch_scc1 .Lpeel_exit_p2

.Lpeel_exit_p2:
	s_and_b64 vcc, exec, s[42:43]
	s_cbranch_vccnz .LBB0_250
	v_lshl_add_u32 v164, s6, 8, v159
	s_cmp_gt_i32 s78, 1
	s_mov_b64 s[6:7], -1
	s_cbranch_scc1 .LBB0_251

.LBB0_545:
	s_cmp_lt_i32 s56, 5
	s_cselect_b64 s[0:1], -1, 0
	s_cmp_gt_i32 s57, 4
	s_cselect_b64 s[4:5], -1, 0
	s_and_b64 s[0:1], s[0:1], s[4:5]
	v_cndmask_b32_e64 v2, 0, 1, s[62:63]
	s_andn2_b64 vcc, exec, s[0:1]
	v_cmp_ne_u32_e64 s[4:5], 1, v2
	s_cbranch_vccnz .LBB0_758
	v_mov_b32_e32 v2, 0
	global_load_dword v249, v2, s[34:35] sc1
	s_mov_b64 s[6:7], -1
	s_and_b64 vcc, exec, s[4:5]
	s_cbranch_vccnz .LBB0_551
	s_lshl_b32 s0, s89, 3
	s_add_i32 s6, s0, s99
	s_cmpk_gt_i32 s6, 0x3fff
	s_cbranch_scc1 .LBB0_550
	v_readlane_b32 s12, v250, 0
	s_ashr_i32 s7, s6, 31
	v_readlane_b32 s18, v250, 6
	v_readlane_b32 s19, v250, 7
	s_lshl_b32 s8, s33, 3
	s_lshl_b64 s[0:1], s[6:7], 12
	s_mov_b64 s[10:11], s[18:19]
	v_readlane_b32 s13, v250, 1
	s_add_u32 s0, s10, s0
	s_mov_b32 s12, 0x7fc00000
	v_lshlrev_b32_e32 v2, 4, v1
	v_mov_b32_e32 v3, 0
	v_readlane_b32 s14, v250, 2
	v_readlane_b32 s15, v250, 3
	s_addc_u32 s1, s11, s1
	s_mov_b32 s13, s12
	v_lshl_add_u64 v[2:3], s[0:1], 0, v[2:3]
	s_mov_b64 s[0:1], 0xc00
	s_ashr_i32 s9, s8, 31
	s_mov_b32 s14, s12
	s_mov_b32 s15, s12
	v_mov_b64_e32 v[4:5], s[12:13]
	v_lshl_add_u64 v[2:3], v[2:3], 0, s[0:1]
	s_lshl_b64 s[10:11], s[8:9], 12
	v_mov_b64_e32 v[6:7], s[14:15]
	v_readlane_b32 s16, v250, 4
	v_readlane_b32 s17, v250, 5

.LBB0_613:
	s_or_b64 exec, exec, s[18:19]
	s_ashr_i32 s12, s14, 31
	s_lshr_b32 s12, s12, 29
	s_add_i32 s12, s14, s12
	s_ashr_i32 s12, s12, 3
	s_mul_hi_i32 s13, s12, 0x6000
	s_mulk_i32 s12, 0x6000
	s_add_u32 s12, s52, s12
	s_addc_u32 s13, s53, s13
	v_lshl_add_u64 v[214:215], v[210:211], 2, s[12:13]
	s_mov_b64 s[12:13], 0x2000
	v_lshl_add_u64 v[190:191], v[214:215], 0, s[12:13]
	s_movk_i32 s12, 0x2000
	v_add_co_u32_e32 v192, vcc, s12, v214
	s_waitcnt lgkmcnt(0)
	s_barrier
	s_nop 0
	v_addc_co_u32_e32 v193, vcc, 0, v215, vcc
	s_mov_b64 s[12:13], 0x2200
	global_load_dwordx4 v[206:209], v[192:193], off
	global_load_dwordx4 v[202:205], v[190:191], off offset:16
	v_lshl_add_u64 v[190:191], v[214:215], 0, s[12:13]
	global_load_dwordx4 v[198:201], v[192:193], off offset:512
	s_nop 0
	global_load_dwordx4 v[190:193], v[190:191], off offset:16
	v_readfirstlane_b32 s46, v249
	s_nop 3
	s_or_b32 s0, s0, s46
	s_cmp_lg_u32 s0, 0
	s_cselect_b64 s[18:19], -1, 0
	s_cmp_eq_u32 s0, 0
	s_cselect_b64 s[26:27], -1, 0
	s_and_b32 s0, s47, 0xffffff00
	s_add_i32 s0, s0, 0
	v_lshl_add_u32 v224, v219, 2, s0
	v_mov_b32_e32 v216, 0x7fc00000
	s_and_b64 vcc, exec, s[26:27]
	v_mov_b32_e32 v218, 0x7fc00000
	s_cbranch_vccz .LBB0_615
	ds_read_b32 v218, v224 offset:8192

.LBB0_767:
	s_ashr_i32 s19, s18, 31
	s_lshl_b64 s[20:21], s[18:19], 19
	s_add_u32 s20, s24, s20
	s_addc_u32 s21, s25, s21
	s_and_b64 s[26:27], s[6:7], exec
	s_cselect_b32 s0, s21, s39
	s_cselect_b32 s19, s20, s38
	s_ashr_i32 s17, s16, 31
	s_lshl_b64 s[26:27], s[16:17], 19
	s_add_u32 s26, s64, s26
	s_addc_u32 s27, s65, s27
	s_and_b64 s[42:43], s[6:7], exec
	s_cselect_b32 s17, s27, s41
	s_cselect_b32 s66, s26, s40
	s_add_u32 s38, s38, 0x40080
	s_addc_u32 s39, s39, 0
	s_add_u32 s67, s40, 0x100
	s_addc_u32 s68, s41, 0
	s_mov_b32 s69, -2
	ds_read_b128 v[146:149], v153
	ds_read_b128 v[156:159], v153 offset:1024
	ds_read_b128 v[160:163], v153 offset:2048
	ds_read_b128 v[164:167], v153 offset:3072
	ds_read_b128 v[168:171], v154
	ds_read_b128 v[172:175], v154 offset:1024
	ds_read_b128 v[176:179], v154 offset:2048
	ds_read_b128 v[180:183], v154 offset:3072
	s_add_u32 s40, s38, 0xfffc0080
	s_addc_u32 s41, s39, -1
	s_cmp_eq_u32 s69, 12
	s_cselect_b32 s43, s0, s41
	s_cselect_b32 s42, s19, s40
	s_cselect_b32 s41, s17, s68
	s_cselect_b32 s40, s66, s67
	v_lshl_add_u64 v[216:217], s[38:39], 0, v[138:139]
	s_add_i32 m0, s29, 0xc000
	ds_read_b128 v[184:187], v155
	ds_read_b128 v[188:191], v155 offset:1024
	ds_read_b128 v[192:195], v155 offset:2048
	ds_read_b128 v[196:199], v155 offset:3072
	ds_read_b128 v[200:203], v155 offset:4096
	ds_read_b128 v[204:207], v155 offset:5120
	ds_read_b128 v[208:211], v155 offset:6144
	ds_read_b128 v[212:215], v155 offset:7168
	global_load_lds_dwordx4 v[216:217], off
	v_lshl_add_u64 v[216:217], s[38:39], 0, v[140:141]
	s_add_i32 m0, s29, 0xe000
	s_nop 0
	global_load_lds_dwordx4 v[216:217], off
	s_waitcnt vmcnt(8)
	s_waitcnt lgkmcnt(0)
	s_setprio 1
	s_waitcnt lgkmcnt(0)
	v_mfma_f32_16x16x32_bf16 v[126:129], v[146:149], v[184:187], 0
	s_barrier
	v_mfma_f32_16x16x32_bf16 v[122:125], v[160:163], v[184:187], 0
	v_mfma_f32_16x16x32_bf16 v[110:113], v[146:149], v[192:195], 0
	v_mfma_f32_16x16x32_bf16 v[106:109], v[160:163], v[192:195], 0
	v_mfma_f32_16x16x32_bf16 v[94:97], v[146:149], v[200:203], 0
	v_mfma_f32_16x16x32_bf16 v[90:93], v[160:163], v[200:203], 0
	v_mfma_f32_16x16x32_bf16 v[78:81], v[146:149], v[208:211], 0
	v_mfma_f32_16x16x32_bf16 v[74:77], v[160:163], v[208:211], 0
	v_mfma_f32_16x16x32_bf16 v[118:121], v[168:171], v[184:187], 0
	v_mfma_f32_16x16x32_bf16 v[114:117], v[176:179], v[184:187], 0
	v_mfma_f32_16x16x32_bf16 v[102:105], v[168:171], v[192:195], 0
	v_mfma_f32_16x16x32_bf16 v[98:101], v[176:179], v[192:195], 0
	v_mfma_f32_16x16x32_bf16 v[86:89], v[168:171], v[200:203], 0
	v_mfma_f32_16x16x32_bf16 v[82:85], v[176:179], v[200:203], 0
	v_mfma_f32_16x16x32_bf16 v[70:73], v[168:171], v[208:211], 0
	v_mfma_f32_16x16x32_bf16 v[66:69], v[176:179], v[208:211], 0
	v_mfma_f32_16x16x32_bf16 v[126:129], v[156:159], v[188:191], v[126:129]
	v_mfma_f32_16x16x32_bf16 v[122:125], v[164:167], v[188:191], v[122:125]
	v_mfma_f32_16x16x32_bf16 v[110:113], v[156:159], v[196:199], v[110:113]
	v_mfma_f32_16x16x32_bf16 v[106:109], v[164:167], v[196:199], v[106:109]
	v_mfma_f32_16x16x32_bf16 v[94:97], v[156:159], v[204:207], v[94:97]
	v_mfma_f32_16x16x32_bf16 v[90:93], v[164:167], v[204:207], v[90:93]
	v_mfma_f32_16x16x32_bf16 v[78:81], v[156:159], v[212:215], v[78:81]
	v_mfma_f32_16x16x32_bf16 v[74:77], v[164:167], v[212:215], v[74:77]
	v_mfma_f32_16x16x32_bf16 v[118:121], v[172:175], v[188:191], v[118:121]
	v_mfma_f32_16x16x32_bf16 v[114:117], v[180:183], v[188:191], v[114:117]
	v_mfma_f32_16x16x32_bf16 v[102:105], v[172:175], v[196:199], v[102:105]
	v_mfma_f32_16x16x32_bf16 v[98:101], v[180:183], v[196:199], v[98:101]
	v_mfma_f32_16x16x32_bf16 v[86:89], v[172:175], v[204:207], v[86:89]
	v_mfma_f32_16x16x32_bf16 v[82:85], v[180:183], v[204:207], v[82:85]
	v_mfma_f32_16x16x32_bf16 v[70:73], v[172:175], v[212:215], v[70:73]
	v_mfma_f32_16x16x32_bf16 v[66:69], v[180:183], v[212:215], v[66:69]
	s_setprio 0
	s_barrier
	s_add_i32 s70, s51, s1
	v_lshl_add_u64 v[216:217], s[40:41], 0, v[134:135]
	s_mov_b32 m0, s70
	ds_read_b128 v[184:187], v155 offset:16384
	ds_read_b128 v[188:191], v155 offset:17408
	ds_read_b128 v[192:195], v155 offset:18432
	ds_read_b128 v[196:199], v155 offset:19456
	ds_read_b128 v[200:203], v155 offset:20480
	ds_read_b128 v[204:207], v155 offset:21504
	ds_read_b128 v[208:211], v155 offset:22528
	ds_read_b128 v[212:215], v155 offset:23552
	global_load_lds_dwordx4 v[216:217], off
	s_add_i32 m0, s70, 0x2000
	s_add_u32 s70, s40, 0x40000
	v_lshl_add_u64 v[218:219], s[40:41], 0, v[130:131]
	s_addc_u32 s71, s41, 0
	s_add_i32 s72, s60, s1
	global_load_lds_dwordx4 v[218:219], off
	v_lshl_add_u64 v[220:221], s[70:71], 0, v[134:135]
	s_mov_b32 m0, s72
	v_lshl_add_u64 v[222:223], s[42:43], 0, v[132:133]
	global_load_lds_dwordx4 v[220:221], off
	v_lshl_add_u64 v[220:221], s[70:71], 0, v[130:131]
	s_add_i32 m0, s72, 0x2000
	s_nop 0
	global_load_lds_dwordx4 v[220:221], off
	v_lshl_add_u64 v[220:221], s[42:43], 0, v[136:137]
	s_mov_b32 m0, s29
	s_nop 0
	global_load_lds_dwordx4 v[220:221], off
	s_mov_b32 m0, s37
	s_nop 0
	global_load_lds_dwordx4 v[222:223], off
	s_waitcnt vmcnt(8)
	s_waitcnt lgkmcnt(0)
	s_setprio 1
	s_waitcnt lgkmcnt(0)
	v_mfma_f32_16x16x32_bf16 v[62:65], v[146:149], v[184:187], 0
	s_barrier
	v_mfma_f32_16x16x32_bf16 v[58:61], v[160:163], v[184:187], 0
	v_mfma_f32_16x16x32_bf16 v[46:49], v[146:149], v[192:195], 0
	v_mfma_f32_16x16x32_bf16 v[42:45], v[160:163], v[192:195], 0
	v_mfma_f32_16x16x32_bf16 v[30:33], v[146:149], v[200:203], 0
	v_mfma_f32_16x16x32_bf16 v[26:29], v[160:163], v[200:203], 0
	v_mfma_f32_16x16x32_bf16 v[14:17], v[146:149], v[208:211], 0
	v_mfma_f32_16x16x32_bf16 v[10:13], v[160:163], v[208:211], 0
	v_mfma_f32_16x16x32_bf16 v[54:57], v[168:171], v[184:187], 0
	v_mfma_f32_16x16x32_bf16 v[50:53], v[176:179], v[184:187], 0
	v_mfma_f32_16x16x32_bf16 v[38:41], v[168:171], v[192:195], 0
	v_mfma_f32_16x16x32_bf16 v[34:37], v[176:179], v[192:195], 0
	v_mfma_f32_16x16x32_bf16 v[22:25], v[168:171], v[200:203], 0
	v_mfma_f32_16x16x32_bf16 v[18:21], v[176:179], v[200:203], 0
	v_mfma_f32_16x16x32_bf16 v[6:9], v[168:171], v[208:211], 0
	v_mfma_f32_16x16x32_bf16 v[2:5], v[176:179], v[208:211], 0
	v_mfma_f32_16x16x32_bf16 v[62:65], v[156:159], v[188:191], v[62:65]
	v_mfma_f32_16x16x32_bf16 v[58:61], v[164:167], v[188:191], v[58:61]
	v_mfma_f32_16x16x32_bf16 v[46:49], v[156:159], v[196:199], v[46:49]
	v_mfma_f32_16x16x32_bf16 v[42:45], v[164:167], v[196:199], v[42:45]
	v_mfma_f32_16x16x32_bf16 v[30:33], v[156:159], v[204:207], v[30:33]
	v_mfma_f32_16x16x32_bf16 v[26:29], v[164:167], v[204:207], v[26:29]
	v_mfma_f32_16x16x32_bf16 v[14:17], v[156:159], v[212:215], v[14:17]
	v_mfma_f32_16x16x32_bf16 v[10:13], v[164:167], v[212:215], v[10:13]
	v_mfma_f32_16x16x32_bf16 v[54:57], v[172:175], v[188:191], v[54:57]
	v_mfma_f32_16x16x32_bf16 v[50:53], v[180:183], v[188:191], v[50:53]
	v_mfma_f32_16x16x32_bf16 v[38:41], v[172:175], v[196:199], v[38:41]
	v_mfma_f32_16x16x32_bf16 v[34:37], v[180:183], v[196:199], v[34:37]
	v_mfma_f32_16x16x32_bf16 v[22:25], v[172:175], v[204:207], v[22:25]
	v_mfma_f32_16x16x32_bf16 v[18:21], v[180:183], v[204:207], v[18:21]
	v_mfma_f32_16x16x32_bf16 v[6:9], v[172:175], v[212:215], v[6:9]
	v_mfma_f32_16x16x32_bf16 v[2:5], v[180:183], v[212:215], v[2:5]
	s_setprio 0
	s_barrier
	s_add_i32 s70, 0, 0x18000
	s_add_i32 s71, 0, 0x1c000
	v_add_u32_e32 v164, s70, v151
	v_add_u32_e32 v180, s71, v151
	ds_read_b128 v[146:149], v164
	ds_read_b128 v[156:159], v164 offset:1024
	ds_read_b128 v[160:163], v164 offset:2048
	ds_read_b128 v[164:167], v164 offset:3072
	ds_read_b128 v[168:171], v180
	ds_read_b128 v[172:175], v180 offset:1024
	ds_read_b128 v[176:179], v180 offset:2048
	ds_read_b128 v[180:183], v180 offset:3072
	s_add_u32 s42, s42, 0x40000
	s_addc_u32 s43, s43, 0
	s_mov_b32 m0, s45
	v_lshl_add_u64 v[224:225], s[42:43], 0, v[136:137]
	ds_read_b128 v[184:187], v155 offset:32768
	ds_read_b128 v[188:191], v155 offset:33792
	ds_read_b128 v[192:195], v155 offset:34816
	ds_read_b128 v[196:199], v155 offset:35840
	ds_read_b128 v[200:203], v155 offset:36864
	ds_read_b128 v[204:207], v155 offset:37888
	ds_read_b128 v[208:211], v155 offset:38912
	ds_read_b128 v[212:215], v155 offset:39936
	global_load_lds_dwordx4 v[224:225], off
	v_lshl_add_u64 v[224:225], s[42:43], 0, v[132:133]
	s_mov_b32 m0, s46
	s_nop 0
	global_load_lds_dwordx4 v[224:225], off
	s_waitcnt vmcnt(8)
	s_waitcnt lgkmcnt(0)
	s_setprio 1
	s_waitcnt lgkmcnt(0)
	v_mfma_f32_16x16x32_bf16 v[126:129], v[146:149], v[184:187], v[126:129]
	s_barrier
	v_mfma_f32_16x16x32_bf16 v[122:125], v[160:163], v[184:187], v[122:125]
	v_mfma_f32_16x16x32_bf16 v[110:113], v[146:149], v[192:195], v[110:113]
	v_mfma_f32_16x16x32_bf16 v[106:109], v[160:163], v[192:195], v[106:109]
	v_mfma_f32_16x16x32_bf16 v[94:97], v[146:149], v[200:203], v[94:97]
	v_mfma_f32_16x16x32_bf16 v[90:93], v[160:163], v[200:203], v[90:93]
	v_mfma_f32_16x16x32_bf16 v[78:81], v[146:149], v[208:211], v[78:81]
	v_mfma_f32_16x16x32_bf16 v[74:77], v[160:163], v[208:211], v[74:77]
	v_mfma_f32_16x16x32_bf16 v[118:121], v[168:171], v[184:187], v[118:121]
	v_mfma_f32_16x16x32_bf16 v[114:117], v[176:179], v[184:187], v[114:117]
	v_mfma_f32_16x16x32_bf16 v[102:105], v[168:171], v[192:195], v[102:105]
	v_mfma_f32_16x16x32_bf16 v[98:101], v[176:179], v[192:195], v[98:101]
	v_mfma_f32_16x16x32_bf16 v[86:89], v[168:171], v[200:203], v[86:89]
	v_mfma_f32_16x16x32_bf16 v[82:85], v[176:179], v[200:203], v[82:85]
	v_mfma_f32_16x16x32_bf16 v[70:73], v[168:171], v[208:211], v[70:73]
	v_mfma_f32_16x16x32_bf16 v[66:69], v[176:179], v[208:211], v[66:69]
	v_mfma_f32_16x16x32_bf16 v[126:129], v[156:159], v[188:191], v[126:129]
	v_mfma_f32_16x16x32_bf16 v[122:125], v[164:167], v[188:191], v[122:125]
	v_mfma_f32_16x16x32_bf16 v[110:113], v[156:159], v[196:199], v[110:113]
	v_mfma_f32_16x16x32_bf16 v[106:109], v[164:167], v[196:199], v[106:109]
	v_mfma_f32_16x16x32_bf16 v[94:97], v[156:159], v[204:207], v[94:97]
	v_mfma_f32_16x16x32_bf16 v[90:93], v[164:167], v[204:207], v[90:93]
	v_mfma_f32_16x16x32_bf16 v[78:81], v[156:159], v[212:215], v[78:81]
	v_mfma_f32_16x16x32_bf16 v[74:77], v[164:167], v[212:215], v[74:77]
	v_mfma_f32_16x16x32_bf16 v[118:121], v[172:175], v[188:191], v[118:121]
	v_mfma_f32_16x16x32_bf16 v[114:117], v[180:183], v[188:191], v[114:117]
	v_mfma_f32_16x16x32_bf16 v[102:105], v[172:175], v[196:199], v[102:105]
	v_mfma_f32_16x16x32_bf16 v[98:101], v[180:183], v[196:199], v[98:101]
	v_mfma_f32_16x16x32_bf16 v[86:89], v[172:175], v[204:207], v[86:89]
	v_mfma_f32_16x16x32_bf16 v[82:85], v[180:183], v[204:207], v[82:85]
	v_mfma_f32_16x16x32_bf16 v[70:73], v[172:175], v[212:215], v[70:73]
	v_mfma_f32_16x16x32_bf16 v[66:69], v[180:183], v[212:215], v[66:69]
	s_setprio 0
	s_barrier
	s_add_i32 s42, s70, s1
	v_lshl_add_u64 v[216:217], v[216:217], 0, s[12:13]
	s_mov_b32 m0, s42
	ds_read_b128 v[184:187], v155 offset:49152
	ds_read_b128 v[188:191], v155 offset:50176
	ds_read_b128 v[192:195], v155 offset:51200
	ds_read_b128 v[196:199], v155 offset:52224
	ds_read_b128 v[200:203], v155 offset:53248
	ds_read_b128 v[204:207], v155 offset:54272
	ds_read_b128 v[208:211], v155 offset:55296
	ds_read_b128 v[212:215], v155 offset:56320
	global_load_lds_dwordx4 v[216:217], off
	s_add_i32 m0, s42, 0x2000
	s_add_u32 s40, s40, 0x40080
	v_lshl_add_u64 v[216:217], v[218:219], 0, s[12:13]
	s_addc_u32 s41, s41, 0
	s_add_i32 s42, s71, s1
	global_load_lds_dwordx4 v[216:217], off
	v_lshl_add_u64 v[216:217], s[40:41], 0, v[134:135]
	s_mov_b32 m0, s42
	s_nop 0
	global_load_lds_dwordx4 v[216:217], off
	v_lshl_add_u64 v[216:217], s[40:41], 0, v[130:131]
	s_add_i32 m0, s42, 0x2000
	s_nop 0
	global_load_lds_dwordx4 v[216:217], off
	v_lshl_add_u64 v[216:217], v[220:221], 0, s[12:13]
	s_mov_b32 m0, s48
	s_nop 0
	global_load_lds_dwordx4 v[216:217], off
	v_lshl_add_u64 v[216:217], v[222:223], 0, s[12:13]
	s_mov_b32 m0, s49
	s_nop 0
	global_load_lds_dwordx4 v[216:217], off
	s_waitcnt vmcnt(8)
	s_waitcnt lgkmcnt(0)
	s_setprio 1
	s_waitcnt lgkmcnt(0)
	v_mfma_f32_16x16x32_bf16 v[62:65], v[146:149], v[184:187], v[62:65]
	s_barrier
	v_mfma_f32_16x16x32_bf16 v[58:61], v[160:163], v[184:187], v[58:61]
	v_mfma_f32_16x16x32_bf16 v[46:49], v[146:149], v[192:195], v[46:49]
	v_mfma_f32_16x16x32_bf16 v[42:45], v[160:163], v[192:195], v[42:45]
	v_mfma_f32_16x16x32_bf16 v[30:33], v[146:149], v[200:203], v[30:33]
	v_mfma_f32_16x16x32_bf16 v[26:29], v[160:163], v[200:203], v[26:29]
	v_mfma_f32_16x16x32_bf16 v[14:17], v[146:149], v[208:211], v[14:17]
	v_mfma_f32_16x16x32_bf16 v[10:13], v[160:163], v[208:211], v[10:13]
	v_mfma_f32_16x16x32_bf16 v[54:57], v[168:171], v[184:187], v[54:57]
	v_mfma_f32_16x16x32_bf16 v[50:53], v[176:179], v[184:187], v[50:53]
	v_mfma_f32_16x16x32_bf16 v[38:41], v[168:171], v[192:195], v[38:41]
	v_mfma_f32_16x16x32_bf16 v[34:37], v[176:179], v[192:195], v[34:37]
	v_mfma_f32_16x16x32_bf16 v[22:25], v[168:171], v[200:203], v[22:25]
	v_mfma_f32_16x16x32_bf16 v[18:21], v[176:179], v[200:203], v[18:21]
	v_mfma_f32_16x16x32_bf16 v[6:9], v[168:171], v[208:211], v[6:9]
	v_mfma_f32_16x16x32_bf16 v[2:5], v[176:179], v[208:211], v[2:5]
	v_mfma_f32_16x16x32_bf16 v[62:65], v[156:159], v[188:191], v[62:65]
	v_mfma_f32_16x16x32_bf16 v[58:61], v[164:167], v[188:191], v[58:61]
	v_mfma_f32_16x16x32_bf16 v[46:49], v[156:159], v[196:199], v[46:49]
	v_mfma_f32_16x16x32_bf16 v[42:45], v[164:167], v[196:199], v[42:45]
	v_mfma_f32_16x16x32_bf16 v[30:33], v[156:159], v[204:207], v[30:33]
	v_mfma_f32_16x16x32_bf16 v[26:29], v[164:167], v[204:207], v[26:29]
	v_mfma_f32_16x16x32_bf16 v[14:17], v[156:159], v[212:215], v[14:17]
	v_mfma_f32_16x16x32_bf16 v[10:13], v[164:167], v[212:215], v[10:13]
	v_mfma_f32_16x16x32_bf16 v[54:57], v[172:175], v[188:191], v[54:57]
	v_mfma_f32_16x16x32_bf16 v[50:53], v[180:183], v[188:191], v[50:53]
	v_mfma_f32_16x16x32_bf16 v[38:41], v[172:175], v[196:199], v[38:41]
	v_mfma_f32_16x16x32_bf16 v[34:37], v[180:183], v[196:199], v[34:37]
	v_mfma_f32_16x16x32_bf16 v[22:25], v[172:175], v[204:207], v[22:25]
	v_mfma_f32_16x16x32_bf16 v[18:21], v[180:183], v[204:207], v[18:21]
	v_mfma_f32_16x16x32_bf16 v[6:9], v[172:175], v[212:215], v[6:9]
	v_mfma_f32_16x16x32_bf16 v[2:5], v[180:183], v[212:215], v[2:5]
	s_setprio 0
	s_barrier
	s_add_i32 s69, s69, 2
	s_add_u32 s38, s38, 0x100
	s_addc_u32 s39, s39, 0
	s_add_u32 s67, s67, 0x100
	s_addc_u32 s68, s68, 0
	s_cmp_gt_u32 s69, 13
	s_cbranch_scc1 .Lpeel_exit_p5

.Lpeel_exit_p5:
	s_and_b64 vcc, exec, s[14:15]
	s_cbranch_vccz .LBB0_771
	s_barrier
